# EpiResid epilogues (out-proj, down): 12 x-loads in flight with counted waits instead of 16-step load/wait/store ladder; + attention PV b64 reads; bias1 loop
# speedup vs baseline: 1.0103x; 1.0086x over previous
.LBB0_689:
	v_lshl_add_u32 v174, s38, 8, v156
	v_lshl_or_b32 v172, s39, 8, v158
	s_ashr_i32 s11, s38, 4
	v_ashrrev_i32_e32 v175, 31, v174
	s_mul_hi_i32 s17, s11, 0xc000
	s_mul_i32 s11, s11, 0xc000
	v_ashrrev_i32_e32 v173, 31, v172
	v_lshlrev_b64 v[130:131], 11, v[174:175]
	s_add_u32 s16, s31, s11
	v_lshl_add_u64 v[130:131], v[130:131], 0, v[172:173]
	v_readlane_b32 s40, v253, 0
	s_addc_u32 s17, s34, s17
	v_lshlrev_b64 v[154:155], 2, v[130:131]
	v_readlane_b32 s41, v253, 1
	v_lshl_add_u64 v[128:129], v[172:173], 2, s[16:17]
	v_lshl_add_u64 v[178:179], s[56:57], 0, v[154:155]
	v_lshl_add_u64 v[176:177], s[40:41], 0, v[154:155]
	flat_load_dwordx4 v[140:143], v[128:129]
	flat_load_dwordx4 v[136:139], v[128:129] offset:16
	flat_load_dwordx4 v[132:135], v[128:129] offset:512
	s_nop 0
	flat_load_dwordx4 v[128:131], v[128:129] offset:528
	s_mov_b64 s[16:17], 0x100000
	s_andn2_b64 vcc, exec, s[4:5]
	s_mov_b64 s[4:5], -1
	v_readlane_b32 s42, v253, 2
	v_readlane_b32 s43, v253, 3
	v_readlane_b32 s44, v253, 4
	v_readlane_b32 s45, v253, 5
	v_readlane_b32 s46, v253, 6
	v_readlane_b32 s47, v253, 7
	v_readlane_b32 s48, v253, 8
	v_readlane_b32 s49, v253, 9
	v_readlane_b32 s50, v253, 10
	v_readlane_b32 s51, v253, 11
	v_readlane_b32 s52, v253, 12
	v_readlane_b32 s53, v253, 13
	v_readlane_b32 s54, v253, 14
	v_readlane_b32 s55, v253, 15
	v_lshl_add_u64 v[222:223], v[176:177], 0, 0
	global_load_dwordx4 v[162:165], v[222:223], off
	global_load_dwordx4 v[168:171], v[222:223], off offset:16
	global_load_dwordx4 v[180:183], v[222:223], off offset:512
	global_load_dwordx4 v[184:187], v[222:223], off offset:528
	s_mov_b64 s[16:17], 0x20000
	v_lshl_add_u64 v[222:223], v[176:177], 0, s[16:17]
	global_load_dwordx4 v[188:191], v[222:223], off
	global_load_dwordx4 v[192:195], v[222:223], off offset:16
	global_load_dwordx4 v[196:199], v[222:223], off offset:512
	global_load_dwordx4 v[210:213], v[222:223], off offset:528
	s_mov_b64 s[16:17], 0x40000
	v_lshl_add_u64 v[222:223], v[176:177], 0, s[16:17]
	global_load_dwordx4 v[214:217], v[222:223], off
	global_load_dwordx4 v[218:221], v[222:223], off offset:16
	global_load_dwordx4 v[226:229], v[222:223], off offset:512
	global_load_dwordx4 v[172:175], v[222:223], off offset:528
	s_waitcnt vmcnt(11) lgkmcnt(0)
	v_pk_fma_f32 v[124:125], v[124:125], v[140:141], v[162:163]
	v_pk_fma_f32 v[126:127], v[126:127], v[142:143], v[164:165]
	v_lshl_add_u64 v[224:225], v[178:179], 0, 0
	global_store_dwordx4 v[224:225], v[124:127], off
	s_mov_b64 s[16:17], 0x60000
	v_lshl_add_u64 v[222:223], v[176:177], 0, s[16:17]
	global_load_dwordx4 v[162:165], v[222:223], off
	s_waitcnt vmcnt(12)
	v_pk_fma_f32 v[120:121], v[120:121], v[136:137], v[168:169]
	v_pk_fma_f32 v[122:123], v[122:123], v[138:139], v[170:171]
	global_store_dwordx4 v[224:225], v[120:123], off offset:16
	global_load_dwordx4 v[168:171], v[222:223], off offset:16
	s_waitcnt vmcnt(13)
	v_pk_fma_f32 v[112:113], v[112:113], v[132:133], v[180:181]
	v_pk_fma_f32 v[114:115], v[114:115], v[134:135], v[182:183]
	global_store_dwordx4 v[224:225], v[112:115], off offset:512
	global_load_dwordx4 v[180:183], v[222:223], off offset:512
	s_waitcnt vmcnt(14)
	v_pk_fma_f32 v[104:105], v[104:105], v[128:129], v[184:185]
	v_pk_fma_f32 v[106:107], v[106:107], v[130:131], v[186:187]
	global_store_dwordx4 v[224:225], v[104:107], off offset:528
	global_load_dwordx4 v[184:187], v[222:223], off offset:528
	s_waitcnt vmcnt(15)
	v_pk_fma_f32 v[116:117], v[116:117], v[140:141], v[188:189]
	v_pk_fma_f32 v[118:119], v[118:119], v[142:143], v[190:191]
	s_mov_b64 s[16:17], 0x20000
	v_lshl_add_u64 v[224:225], v[178:179], 0, s[16:17]
	global_store_dwordx4 v[224:225], v[116:119], off
	s_mov_b64 s[16:17], 0x100000
	v_lshl_add_u64 v[222:223], v[176:177], 0, s[16:17]
	global_load_dwordx4 v[188:191], v[222:223], off
	s_waitcnt vmcnt(16)
	v_pk_fma_f32 v[108:109], v[108:109], v[136:137], v[192:193]
	v_pk_fma_f32 v[110:111], v[110:111], v[138:139], v[194:195]
	global_store_dwordx4 v[224:225], v[108:111], off offset:16
	global_load_dwordx4 v[192:195], v[222:223], off offset:16
	s_waitcnt vmcnt(17)
	v_pk_fma_f32 v[96:97], v[96:97], v[132:133], v[196:197]
	v_pk_fma_f32 v[98:99], v[98:99], v[134:135], v[198:199]
	global_store_dwordx4 v[224:225], v[96:99], off offset:512
	global_load_dwordx4 v[196:199], v[222:223], off offset:512
	s_waitcnt vmcnt(18)
	v_pk_fma_f32 v[88:89], v[88:89], v[128:129], v[210:211]
	v_pk_fma_f32 v[90:91], v[90:91], v[130:131], v[212:213]
	global_store_dwordx4 v[224:225], v[88:91], off offset:528
	global_load_dwordx4 v[210:213], v[222:223], off offset:528
	s_waitcnt vmcnt(19)
	v_pk_fma_f32 v[100:101], v[100:101], v[140:141], v[214:215]
	v_pk_fma_f32 v[102:103], v[102:103], v[142:143], v[216:217]
	s_mov_b64 s[16:17], 0x40000
	v_lshl_add_u64 v[224:225], v[178:179], 0, s[16:17]
	global_store_dwordx4 v[224:225], v[100:103], off
	s_mov_b64 s[16:17], 0x120000
	v_lshl_add_u64 v[222:223], v[176:177], 0, s[16:17]
	global_load_dwordx4 v[214:217], v[222:223], off
	s_waitcnt vmcnt(20)
	v_pk_fma_f32 v[92:93], v[92:93], v[136:137], v[218:219]
	v_pk_fma_f32 v[94:95], v[94:95], v[138:139], v[220:221]
	global_store_dwordx4 v[224:225], v[92:95], off offset:16
	global_load_dwordx4 v[218:221], v[222:223], off offset:16
	s_waitcnt vmcnt(21)
	v_pk_fma_f32 v[80:81], v[80:81], v[132:133], v[226:227]
	v_pk_fma_f32 v[82:83], v[82:83], v[134:135], v[228:229]
	global_store_dwordx4 v[224:225], v[80:83], off offset:512
	global_load_dwordx4 v[226:229], v[222:223], off offset:512
	s_waitcnt vmcnt(22)
	v_pk_fma_f32 v[72:73], v[72:73], v[128:129], v[172:173]
	v_pk_fma_f32 v[74:75], v[74:75], v[130:131], v[174:175]
	global_store_dwordx4 v[224:225], v[72:75], off offset:528
	global_load_dwordx4 v[172:175], v[222:223], off offset:528
	s_waitcnt vmcnt(22)
	v_pk_fma_f32 v[84:85], v[84:85], v[140:141], v[162:163]
	v_pk_fma_f32 v[86:87], v[86:87], v[142:143], v[164:165]
	s_mov_b64 s[16:17], 0x60000
	v_lshl_add_u64 v[224:225], v[178:179], 0, s[16:17]
	global_store_dwordx4 v[224:225], v[84:87], off
	s_mov_b64 s[16:17], 0x140000
	v_lshl_add_u64 v[222:223], v[176:177], 0, s[16:17]
	global_load_dwordx4 v[162:165], v[222:223], off
	s_waitcnt vmcnt(22)
	v_pk_fma_f32 v[76:77], v[76:77], v[136:137], v[168:169]
	v_pk_fma_f32 v[78:79], v[78:79], v[138:139], v[170:171]
	global_store_dwordx4 v[224:225], v[76:79], off offset:16
	global_load_dwordx4 v[168:171], v[222:223], off offset:16
	s_waitcnt vmcnt(22)
	v_pk_fma_f32 v[68:69], v[68:69], v[132:133], v[180:181]
	v_pk_fma_f32 v[70:71], v[70:71], v[134:135], v[182:183]
	global_store_dwordx4 v[224:225], v[68:71], off offset:512
	global_load_dwordx4 v[180:183], v[222:223], off offset:512
	s_waitcnt vmcnt(22)
	v_pk_fma_f32 v[64:65], v[64:65], v[128:129], v[184:185]
	v_pk_fma_f32 v[66:67], v[66:67], v[130:131], v[186:187]
	global_store_dwordx4 v[224:225], v[64:67], off offset:528
	global_load_dwordx4 v[184:187], v[222:223], off offset:528
	s_waitcnt vmcnt(22)
	v_pk_fma_f32 v[60:61], v[60:61], v[140:141], v[188:189]
	v_pk_fma_f32 v[62:63], v[62:63], v[142:143], v[190:191]
	s_mov_b64 s[16:17], 0x100000
	v_lshl_add_u64 v[224:225], v[178:179], 0, s[16:17]
	global_store_dwordx4 v[224:225], v[60:63], off
	s_mov_b64 s[16:17], 0x160000
	v_lshl_add_u64 v[222:223], v[176:177], 0, s[16:17]
	global_load_dwordx4 v[188:191], v[222:223], off
	s_waitcnt vmcnt(22)
	v_pk_fma_f32 v[56:57], v[56:57], v[136:137], v[192:193]
	v_pk_fma_f32 v[58:59], v[58:59], v[138:139], v[194:195]
	global_store_dwordx4 v[224:225], v[56:59], off offset:16
	global_load_dwordx4 v[192:195], v[222:223], off offset:16
	s_waitcnt vmcnt(22)
	v_pk_fma_f32 v[48:49], v[48:49], v[132:133], v[196:197]
	v_pk_fma_f32 v[50:51], v[50:51], v[134:135], v[198:199]
	global_store_dwordx4 v[224:225], v[48:51], off offset:512
	global_load_dwordx4 v[196:199], v[222:223], off offset:512
	s_waitcnt vmcnt(22)
	v_pk_fma_f32 v[40:41], v[40:41], v[128:129], v[210:211]
	v_pk_fma_f32 v[42:43], v[42:43], v[130:131], v[212:213]
	global_store_dwordx4 v[224:225], v[40:43], off offset:528
	global_load_dwordx4 v[210:213], v[222:223], off offset:528
	s_waitcnt vmcnt(22)
	v_pk_fma_f32 v[52:53], v[52:53], v[140:141], v[214:215]
	v_pk_fma_f32 v[54:55], v[54:55], v[142:143], v[216:217]
	s_mov_b64 s[16:17], 0x120000
	v_lshl_add_u64 v[224:225], v[178:179], 0, s[16:17]
	global_store_dwordx4 v[224:225], v[52:55], off
	s_waitcnt vmcnt(21)
	v_pk_fma_f32 v[44:45], v[44:45], v[136:137], v[218:219]
	v_pk_fma_f32 v[46:47], v[46:47], v[138:139], v[220:221]
	global_store_dwordx4 v[224:225], v[44:47], off offset:16
	s_waitcnt vmcnt(20)
	v_pk_fma_f32 v[32:33], v[32:33], v[132:133], v[226:227]
	v_pk_fma_f32 v[34:35], v[34:35], v[134:135], v[228:229]
	global_store_dwordx4 v[224:225], v[32:35], off offset:512
	s_waitcnt vmcnt(19)
	v_pk_fma_f32 v[24:25], v[24:25], v[128:129], v[172:173]
	v_pk_fma_f32 v[26:27], v[26:27], v[130:131], v[174:175]
	global_store_dwordx4 v[224:225], v[24:27], off offset:528
	s_waitcnt vmcnt(18)
	v_pk_fma_f32 v[36:37], v[36:37], v[140:141], v[162:163]
	v_pk_fma_f32 v[38:39], v[38:39], v[142:143], v[164:165]
	s_mov_b64 s[16:17], 0x140000
	v_lshl_add_u64 v[224:225], v[178:179], 0, s[16:17]
	global_store_dwordx4 v[224:225], v[36:39], off
	s_waitcnt vmcnt(17)
	v_pk_fma_f32 v[28:29], v[28:29], v[136:137], v[168:169]
	v_pk_fma_f32 v[30:31], v[30:31], v[138:139], v[170:171]
	global_store_dwordx4 v[224:225], v[28:31], off offset:16
	s_waitcnt vmcnt(16)
	v_pk_fma_f32 v[16:17], v[16:17], v[132:133], v[180:181]
	v_pk_fma_f32 v[18:19], v[18:19], v[134:135], v[182:183]
	global_store_dwordx4 v[224:225], v[16:19], off offset:512
	s_waitcnt vmcnt(15)
	v_pk_fma_f32 v[8:9], v[8:9], v[128:129], v[184:185]
	v_pk_fma_f32 v[10:11], v[10:11], v[130:131], v[186:187]
	global_store_dwordx4 v[224:225], v[8:11], off offset:528
	s_waitcnt vmcnt(14)
	v_pk_fma_f32 v[20:21], v[20:21], v[140:141], v[188:189]
	v_pk_fma_f32 v[22:23], v[22:23], v[142:143], v[190:191]
	s_mov_b64 s[16:17], 0x160000
	v_lshl_add_u64 v[224:225], v[178:179], 0, s[16:17]
	global_store_dwordx4 v[224:225], v[20:23], off
	s_waitcnt vmcnt(13)
	v_pk_fma_f32 v[12:13], v[12:13], v[136:137], v[192:193]
	v_pk_fma_f32 v[14:15], v[14:15], v[138:139], v[194:195]
	global_store_dwordx4 v[224:225], v[12:15], off offset:16
	s_waitcnt vmcnt(12)
	v_pk_fma_f32 v[4:5], v[4:5], v[132:133], v[196:197]
	v_pk_fma_f32 v[6:7], v[6:7], v[134:135], v[198:199]
	global_store_dwordx4 v[224:225], v[4:7], off offset:512
	s_waitcnt vmcnt(11)
	v_pk_fma_f32 v[0:1], v[0:1], v[128:129], v[210:211]
	v_pk_fma_f32 v[2:3], v[2:3], v[130:131], v[212:213]
	global_store_dwordx4 v[224:225], v[0:3], off offset:528
	s_mov_b64 s[16:17], 0x160000
	s_mov_b64 s[16:17], 0x120000
	s_mov_b64 s[16:17], 0x140000
	s_mov_b64 s[16:17], 0x160000
	s_cbranch_vccnz .LBB0_678
	s_andn2_b64 vcc, exec, s[6:7]
	s_cbranch_vccnz .LBB0_677
	s_barrier
	s_branch .LBB0_677

.LBB0_909:
	s_ashr_i32 s12, s35, 4
	v_lshl_add_u32 v174, s35, 8, v156
	v_lshl_or_b32 v48, s36, 8, v158
	s_mul_hi_i32 s13, s12, 0xc000
	s_mul_i32 s12, s12, 0xc000
	v_ashrrev_i32_e32 v175, 31, v174
	s_add_u32 s12, s27, s12
	v_ashrrev_i32_e32 v49, 31, v48
	v_lshlrev_b64 v[154:155], 13, v[174:175]
	s_addc_u32 s13, s28, s13
	v_lshlrev_b64 v[172:173], 2, v[48:49]
	v_lshl_add_u64 v[154:155], s[56:57], 0, v[154:155]
	v_lshl_add_u64 v[48:49], s[12:13], 0, v[172:173]
	v_lshl_add_u64 v[154:155], v[154:155], 0, v[172:173]
	flat_load_dwordx4 v[76:79], v[48:49]
	flat_load_dwordx4 v[72:75], v[48:49] offset:16
	flat_load_dwordx4 v[52:55], v[48:49] offset:512
	s_nop 0
	flat_load_dwordx4 v[48:51], v[48:49] offset:528
	s_nop 0
	s_mov_b64 s[12:13], 0x100000
	v_lshl_add_u64 v[222:223], v[154:155], 0, 0
	global_load_dwordx4 v[162:165], v[222:223], off
	global_load_dwordx4 v[168:171], v[222:223], off offset:16
	global_load_dwordx4 v[176:179], v[222:223], off offset:528
	global_load_dwordx4 v[180:183], v[222:223], off offset:512
	s_mov_b64 s[12:13], 0x20000
	v_lshl_add_u64 v[222:223], v[154:155], 0, s[12:13]
	global_load_dwordx4 v[184:187], v[222:223], off
	global_load_dwordx4 v[188:191], v[222:223], off offset:16
	global_load_dwordx4 v[192:195], v[222:223], off offset:528
	global_load_dwordx4 v[196:199], v[222:223], off offset:512
	s_mov_b64 s[12:13], 0x40000
	v_lshl_add_u64 v[222:223], v[154:155], 0, s[12:13]
	global_load_dwordx4 v[210:213], v[222:223], off
	global_load_dwordx4 v[214:217], v[222:223], off offset:16
	global_load_dwordx4 v[218:221], v[222:223], off offset:528
	global_load_dwordx4 v[226:229], v[222:223], off offset:512
	s_waitcnt vmcnt(11) lgkmcnt(0)
	v_pk_fma_f32 v[140:141], v[140:141], v[76:77], v[162:163]
	v_pk_fma_f32 v[142:143], v[142:143], v[78:79], v[164:165]
	v_lshl_add_u64 v[224:225], v[154:155], 0, 0
	global_store_dwordx4 v[224:225], v[140:143], off
	s_mov_b64 s[12:13], 0x60000
	v_lshl_add_u64 v[222:223], v[154:155], 0, s[12:13]
	global_load_dwordx4 v[162:165], v[222:223], off
	s_waitcnt vmcnt(12)
	v_pk_fma_f32 v[136:137], v[136:137], v[72:73], v[168:169]
	v_pk_fma_f32 v[138:139], v[138:139], v[74:75], v[170:171]
	global_store_dwordx4 v[224:225], v[136:139], off offset:16
	global_load_dwordx4 v[168:171], v[222:223], off offset:16
	s_waitcnt vmcnt(13)
	v_pk_fma_f32 v[128:129], v[128:129], v[48:49], v[176:177]
	v_pk_fma_f32 v[130:131], v[130:131], v[50:51], v[178:179]
	global_store_dwordx4 v[224:225], v[128:131], off offset:528
	global_load_dwordx4 v[176:179], v[222:223], off offset:528
	s_waitcnt vmcnt(14)
	v_pk_fma_f32 v[132:133], v[132:133], v[52:53], v[180:181]
	v_pk_fma_f32 v[134:135], v[134:135], v[54:55], v[182:183]
	global_store_dwordx4 v[224:225], v[132:135], off offset:512
	global_load_dwordx4 v[180:183], v[222:223], off offset:512
	s_waitcnt vmcnt(15)
	v_pk_fma_f32 v[124:125], v[124:125], v[76:77], v[184:185]
	v_pk_fma_f32 v[126:127], v[126:127], v[78:79], v[186:187]
	s_mov_b64 s[12:13], 0x20000
	v_lshl_add_u64 v[224:225], v[154:155], 0, s[12:13]
	global_store_dwordx4 v[224:225], v[124:127], off
	s_mov_b64 s[12:13], 0x100000
	v_lshl_add_u64 v[222:223], v[154:155], 0, s[12:13]
	global_load_dwordx4 v[184:187], v[222:223], off
	s_waitcnt vmcnt(16)
	v_pk_fma_f32 v[120:121], v[120:121], v[72:73], v[188:189]
	v_pk_fma_f32 v[122:123], v[122:123], v[74:75], v[190:191]
	global_store_dwordx4 v[224:225], v[120:123], off offset:16
	global_load_dwordx4 v[188:191], v[222:223], off offset:16
	s_waitcnt vmcnt(17)
	v_pk_fma_f32 v[104:105], v[104:105], v[48:49], v[192:193]
	v_pk_fma_f32 v[106:107], v[106:107], v[50:51], v[194:195]
	global_store_dwordx4 v[224:225], v[104:107], off offset:528
	global_load_dwordx4 v[192:195], v[222:223], off offset:512
	s_waitcnt vmcnt(18)
	v_pk_fma_f32 v[108:109], v[108:109], v[52:53], v[196:197]
	v_pk_fma_f32 v[110:111], v[110:111], v[54:55], v[198:199]
	global_store_dwordx4 v[224:225], v[108:111], off offset:512
	global_load_dwordx4 v[196:199], v[222:223], off offset:528
	s_waitcnt vmcnt(19)
	v_pk_fma_f32 v[116:117], v[116:117], v[76:77], v[210:211]
	v_pk_fma_f32 v[118:119], v[118:119], v[78:79], v[212:213]
	s_mov_b64 s[12:13], 0x40000
	v_lshl_add_u64 v[224:225], v[154:155], 0, s[12:13]
	global_store_dwordx4 v[224:225], v[116:119], off
	s_mov_b64 s[12:13], 0x120000
	v_lshl_add_u64 v[222:223], v[154:155], 0, s[12:13]
	global_load_dwordx4 v[210:213], v[222:223], off
	s_waitcnt vmcnt(20)
	v_pk_fma_f32 v[112:113], v[112:113], v[72:73], v[214:215]
	v_pk_fma_f32 v[114:115], v[114:115], v[74:75], v[216:217]
	global_store_dwordx4 v[224:225], v[112:115], off offset:16
	global_load_dwordx4 v[214:217], v[222:223], off offset:16
	s_waitcnt vmcnt(21)
	v_pk_fma_f32 v[88:89], v[88:89], v[48:49], v[218:219]
	v_pk_fma_f32 v[90:91], v[90:91], v[50:51], v[220:221]
	global_store_dwordx4 v[224:225], v[88:91], off offset:528
	global_load_dwordx4 v[218:221], v[222:223], off offset:528
	s_waitcnt vmcnt(22)
	v_pk_fma_f32 v[92:93], v[92:93], v[52:53], v[226:227]
	v_pk_fma_f32 v[94:95], v[94:95], v[54:55], v[228:229]
	global_store_dwordx4 v[224:225], v[92:95], off offset:512
	global_load_dwordx4 v[226:229], v[222:223], off offset:512
	s_waitcnt vmcnt(22)
	v_pk_fma_f32 v[100:101], v[100:101], v[76:77], v[162:163]
	v_pk_fma_f32 v[102:103], v[102:103], v[78:79], v[164:165]
	s_mov_b64 s[12:13], 0x60000
	v_lshl_add_u64 v[224:225], v[154:155], 0, s[12:13]
	global_store_dwordx4 v[224:225], v[100:103], off
	s_mov_b64 s[12:13], 0x140000
	v_lshl_add_u64 v[222:223], v[154:155], 0, s[12:13]
	global_load_dwordx4 v[162:165], v[222:223], off
	s_waitcnt vmcnt(22)
	v_pk_fma_f32 v[96:97], v[96:97], v[72:73], v[168:169]
	v_pk_fma_f32 v[98:99], v[98:99], v[74:75], v[170:171]
	global_store_dwordx4 v[224:225], v[96:99], off offset:16
	global_load_dwordx4 v[168:171], v[222:223], off offset:16
	s_waitcnt vmcnt(22)
	v_pk_fma_f32 v[80:81], v[80:81], v[48:49], v[176:177]
	v_pk_fma_f32 v[82:83], v[82:83], v[50:51], v[178:179]
	global_store_dwordx4 v[224:225], v[80:83], off offset:528
	global_load_dwordx4 v[176:179], v[222:223], off offset:528
	s_waitcnt vmcnt(22)
	v_pk_fma_f32 v[84:85], v[84:85], v[52:53], v[180:181]
	v_pk_fma_f32 v[86:87], v[86:87], v[54:55], v[182:183]
	global_store_dwordx4 v[224:225], v[84:87], off offset:512
	global_load_dwordx4 v[180:183], v[222:223], off offset:512
	s_waitcnt vmcnt(22)
	v_pk_fma_f32 v[68:69], v[68:69], v[76:77], v[184:185]
	v_pk_fma_f32 v[70:71], v[70:71], v[78:79], v[186:187]
	s_mov_b64 s[12:13], 0x100000
	v_lshl_add_u64 v[224:225], v[154:155], 0, s[12:13]
	global_store_dwordx4 v[224:225], v[68:71], off
	s_mov_b64 s[12:13], 0x160000
	v_lshl_add_u64 v[222:223], v[154:155], 0, s[12:13]
	global_load_dwordx4 v[184:187], v[222:223], off
	s_waitcnt vmcnt(22)
	v_pk_fma_f32 v[64:65], v[64:65], v[72:73], v[188:189]
	v_pk_fma_f32 v[66:67], v[66:67], v[74:75], v[190:191]
	global_store_dwordx4 v[224:225], v[64:67], off offset:16
	global_load_dwordx4 v[188:191], v[222:223], off offset:16
	s_waitcnt vmcnt(22)
	v_pk_fma_f32 v[60:61], v[60:61], v[52:53], v[192:193]
	v_pk_fma_f32 v[62:63], v[62:63], v[54:55], v[194:195]
	global_store_dwordx4 v[224:225], v[60:63], off offset:512
	global_load_dwordx4 v[192:195], v[222:223], off offset:512
	s_waitcnt vmcnt(22)
	v_pk_fma_f32 v[56:57], v[56:57], v[48:49], v[196:197]
	v_pk_fma_f32 v[58:59], v[58:59], v[50:51], v[198:199]
	global_store_dwordx4 v[224:225], v[56:59], off offset:528
	global_load_dwordx4 v[196:199], v[222:223], off offset:528
	s_waitcnt vmcnt(22)
	v_pk_fma_f32 v[44:45], v[44:45], v[76:77], v[210:211]
	v_pk_fma_f32 v[46:47], v[46:47], v[78:79], v[212:213]
	s_mov_b64 s[12:13], 0x120000
	v_lshl_add_u64 v[224:225], v[154:155], 0, s[12:13]
	global_store_dwordx4 v[224:225], v[44:47], off
	s_waitcnt vmcnt(21)
	v_pk_fma_f32 v[40:41], v[40:41], v[72:73], v[214:215]
	v_pk_fma_f32 v[42:43], v[42:43], v[74:75], v[216:217]
	global_store_dwordx4 v[224:225], v[40:43], off offset:16
	s_waitcnt vmcnt(20)
	v_pk_fma_f32 v[32:33], v[32:33], v[48:49], v[218:219]
	v_pk_fma_f32 v[34:35], v[34:35], v[50:51], v[220:221]
	global_store_dwordx4 v[224:225], v[32:35], off offset:528
	s_waitcnt vmcnt(19)
	v_pk_fma_f32 v[36:37], v[36:37], v[52:53], v[226:227]
	v_pk_fma_f32 v[38:39], v[38:39], v[54:55], v[228:229]
	global_store_dwordx4 v[224:225], v[36:39], off offset:512
	s_waitcnt vmcnt(18)
	v_pk_fma_f32 v[28:29], v[28:29], v[76:77], v[162:163]
	v_pk_fma_f32 v[30:31], v[30:31], v[78:79], v[164:165]
	s_mov_b64 s[12:13], 0x140000
	v_lshl_add_u64 v[224:225], v[154:155], 0, s[12:13]
	global_store_dwordx4 v[224:225], v[28:31], off
	s_waitcnt vmcnt(17)
	v_pk_fma_f32 v[24:25], v[24:25], v[72:73], v[168:169]
	v_pk_fma_f32 v[26:27], v[26:27], v[74:75], v[170:171]
	global_store_dwordx4 v[224:225], v[24:27], off offset:16
	s_waitcnt vmcnt(16)
	v_pk_fma_f32 v[16:17], v[16:17], v[48:49], v[176:177]
	v_pk_fma_f32 v[18:19], v[18:19], v[50:51], v[178:179]
	global_store_dwordx4 v[224:225], v[16:19], off offset:528
	s_waitcnt vmcnt(15)
	v_pk_fma_f32 v[20:21], v[20:21], v[52:53], v[180:181]
	v_pk_fma_f32 v[22:23], v[22:23], v[54:55], v[182:183]
	global_store_dwordx4 v[224:225], v[20:23], off offset:512
	s_waitcnt vmcnt(14)
	v_pk_fma_f32 v[12:13], v[12:13], v[76:77], v[184:185]
	v_pk_fma_f32 v[14:15], v[14:15], v[78:79], v[186:187]
	s_mov_b64 s[12:13], 0x160000
	v_lshl_add_u64 v[224:225], v[154:155], 0, s[12:13]
	global_store_dwordx4 v[224:225], v[12:15], off
	s_waitcnt vmcnt(13)
	v_pk_fma_f32 v[8:9], v[8:9], v[72:73], v[188:189]
	v_pk_fma_f32 v[10:11], v[10:11], v[74:75], v[190:191]
	global_store_dwordx4 v[224:225], v[8:11], off offset:16
	s_waitcnt vmcnt(12)
	v_pk_fma_f32 v[4:5], v[4:5], v[52:53], v[192:193]
	v_pk_fma_f32 v[6:7], v[6:7], v[54:55], v[194:195]
	global_store_dwordx4 v[224:225], v[4:7], off offset:512
	s_waitcnt vmcnt(11)
	v_pk_fma_f32 v[0:1], v[0:1], v[48:49], v[196:197]
	v_pk_fma_f32 v[2:3], v[2:3], v[50:51], v[198:199]
	global_store_dwordx4 v[224:225], v[0:3], off offset:528
	s_mov_b64 s[12:13], 0x160000
	s_mov_b32 s12, 0x100000
	s_mov_b64 s[12:13], 0x120000
	s_mov_b32 s12, 0x120000
	s_mov_b64 s[12:13], 0x140000
	s_mov_b32 s12, 0x140000
	s_mov_b64 s[12:13], 0x160000
	s_mov_b32 s12, 0x160000
	s_mov_b64 s[12:13], -1
	s_andn2_b64 vcc, exec, s[2:3]
	s_cbranch_vccnz .LBB0_898
	s_andn2_b64 vcc, exec, s[4:5]
	s_cbranch_vccnz .LBB0_897
	s_barrier
	s_branch .LBB0_897
